# P6 GEMM-1 K-loop back edge rotated as in P2 (counter/next-pointer SALU ahead of the closing barrier), on top of v78
# baseline (speedup 1.0000x reference)
.Lp6_rot:
	s_add_i32 s51, 0, 0x10000
	v_add_u32_e32 v144, s51, v218
	ds_read_b128 v[132:135], v144
	ds_read_b128 v[136:139], v144 offset:1024
	ds_read_b128 v[140:143], v144 offset:2048
	ds_read_b128 v[144:147], v144 offset:3072
	s_cmp_eq_u32 s42, s24
	s_cselect_b32 s24, s20, s26
	s_cselect_b32 s25, s21, s25
	s_cselect_b32 s27, s23, s49
	s_cselect_b32 s26, s22, s19
	v_lshl_add_u64 v[164:165], s[8:9], 0, v[192:193]
	s_add_i32 m0, s35, 0xc000
	ds_read_b128 v[148:151], v220
	ds_read_b128 v[152:155], v220 offset:1024
	ds_read_b128 v[156:159], v220 offset:2048
	ds_read_b128 v[160:163], v220 offset:3072
	ds_read_b128 v[194:197], v220 offset:4096
	ds_read_b128 v[198:201], v220 offset:5120
	ds_read_b128 v[202:205], v220 offset:6144
	ds_read_b128 v[224:227], v220 offset:7168
	global_load_lds_dwordx4 v[164:165], off
	v_lshl_add_u64 v[164:165], s[8:9], 0, v[190:191]
	s_add_i32 m0, s35, 0xe000
	s_nop 0
	global_load_lds_dwordx4 v[164:165], off
	s_waitcnt lgkmcnt(8)
	s_waitcnt vmcnt(10)
	s_barrier
	s_waitcnt lgkmcnt(0)
	s_setprio 1
	s_waitcnt lgkmcnt(0)
	v_mfma_f32_16x16x32_bf16 v[128:131], v[132:135], v[148:151], v[128:131]
	v_mfma_f32_16x16x32_bf16 v[124:127], v[140:143], v[148:151], v[124:127]
	v_mfma_f32_16x16x32_bf16 v[112:115], v[132:135], v[156:159], v[112:115]
	v_mfma_f32_16x16x32_bf16 v[108:111], v[140:143], v[156:159], v[108:111]
	v_mfma_f32_16x16x32_bf16 v[96:99], v[132:135], v[194:197], v[96:99]
	v_mfma_f32_16x16x32_bf16 v[92:95], v[140:143], v[194:197], v[92:95]
	v_mfma_f32_16x16x32_bf16 v[76:79], v[132:135], v[202:205], v[76:79]
	v_mfma_f32_16x16x32_bf16 v[72:75], v[140:143], v[202:205], v[72:75]
	v_mfma_f32_16x16x32_bf16 v[128:131], v[136:139], v[152:155], v[128:131]
	v_mfma_f32_16x16x32_bf16 v[124:127], v[144:147], v[152:155], v[124:127]
	v_mfma_f32_16x16x32_bf16 v[112:115], v[136:139], v[160:163], v[112:115]
	v_mfma_f32_16x16x32_bf16 v[108:111], v[144:147], v[160:163], v[108:111]
	v_mfma_f32_16x16x32_bf16 v[96:99], v[136:139], v[198:201], v[96:99]
	v_mfma_f32_16x16x32_bf16 v[92:95], v[144:147], v[198:201], v[92:95]
	v_mfma_f32_16x16x32_bf16 v[76:79], v[136:139], v[224:227], v[76:79]
	v_mfma_f32_16x16x32_bf16 v[72:75], v[144:147], v[224:227], v[72:75]
	s_setprio 0
	s_barrier
	s_add_i32 s52, 0, 0x14000
	v_add_u32_e32 v164, s52, v218
	s_add_i32 s51, s51, s34
	ds_read_b128 v[228:231], v164
	ds_read_b128 v[232:235], v164 offset:1024
	ds_read_b128 v[236:239], v164 offset:2048
	ds_read_b128 v[240:243], v164 offset:3072
	v_lshl_add_u64 v[164:165], s[26:27], 0, v[182:183]
	s_mov_b32 m0, s51
	v_lshl_add_u64 v[170:171], s[26:27], 0, v[178:179]
	global_load_lds_dwordx4 v[164:165], off
	s_add_i32 m0, s51, 0x2000
	s_nop 0
	global_load_lds_dwordx4 v[170:171], off
	s_waitcnt vmcnt(10)
	s_barrier
	s_waitcnt lgkmcnt(0)
	s_setprio 1
	s_waitcnt lgkmcnt(0)
	v_mfma_f32_16x16x32_bf16 v[120:123], v[228:231], v[148:151], v[120:123]
	v_mfma_f32_16x16x32_bf16 v[116:119], v[236:239], v[148:151], v[116:119]
	v_mfma_f32_16x16x32_bf16 v[104:107], v[228:231], v[156:159], v[104:107]
	v_mfma_f32_16x16x32_bf16 v[100:103], v[236:239], v[156:159], v[100:103]
	v_mfma_f32_16x16x32_bf16 v[88:91], v[228:231], v[194:197], v[88:91]
	v_mfma_f32_16x16x32_bf16 v[84:87], v[236:239], v[194:197], v[84:87]
	v_mfma_f32_16x16x32_bf16 v[68:71], v[228:231], v[202:205], v[68:71]
	v_mfma_f32_16x16x32_bf16 v[64:67], v[236:239], v[202:205], v[64:67]
	v_mfma_f32_16x16x32_bf16 v[120:123], v[232:235], v[152:155], v[120:123]
	v_mfma_f32_16x16x32_bf16 v[116:119], v[240:243], v[152:155], v[116:119]
	v_mfma_f32_16x16x32_bf16 v[104:107], v[232:235], v[160:163], v[104:107]
	v_mfma_f32_16x16x32_bf16 v[100:103], v[240:243], v[160:163], v[100:103]
	v_mfma_f32_16x16x32_bf16 v[88:91], v[232:235], v[198:201], v[88:91]
	v_mfma_f32_16x16x32_bf16 v[84:87], v[240:243], v[198:201], v[84:87]
	v_mfma_f32_16x16x32_bf16 v[68:71], v[232:235], v[224:227], v[68:71]
	v_mfma_f32_16x16x32_bf16 v[64:67], v[240:243], v[224:227], v[64:67]
	s_setprio 0
	s_mov_b32 m0, s35
	v_lshl_add_u64 v[172:173], s[24:25], 0, v[184:185]
	s_barrier
	ds_read_b128 v[148:151], v220 offset:16384
	ds_read_b128 v[152:155], v220 offset:17408
	ds_read_b128 v[156:159], v220 offset:18432
	ds_read_b128 v[160:163], v220 offset:19456
	ds_read_b128 v[194:197], v220 offset:20480
	ds_read_b128 v[198:201], v220 offset:21504
	ds_read_b128 v[202:205], v220 offset:22528
	ds_read_b128 v[224:227], v220 offset:23552
	global_load_lds_dwordx4 v[172:173], off
	v_lshl_add_u64 v[206:207], s[24:25], 0, v[180:181]
	s_mov_b32 m0, s36
	s_nop 0
	global_load_lds_dwordx4 v[206:207], off
	s_barrier
	s_waitcnt lgkmcnt(0)
	s_setprio 1
	s_waitcnt lgkmcnt(0)
	v_mfma_f32_16x16x32_bf16 v[60:63], v[132:135], v[148:151], v[60:63]
	v_mfma_f32_16x16x32_bf16 v[56:59], v[140:143], v[148:151], v[56:59]
	v_mfma_f32_16x16x32_bf16 v[44:47], v[132:135], v[156:159], v[44:47]
	v_mfma_f32_16x16x32_bf16 v[40:43], v[140:143], v[156:159], v[40:43]
	v_mfma_f32_16x16x32_bf16 v[28:31], v[132:135], v[194:197], v[28:31]
	v_mfma_f32_16x16x32_bf16 v[24:27], v[140:143], v[194:197], v[24:27]
	v_mfma_f32_16x16x32_bf16 v[12:15], v[132:135], v[202:205], v[12:15]
	v_mfma_f32_16x16x32_bf16 v[8:11], v[140:143], v[202:205], v[8:11]
	v_mfma_f32_16x16x32_bf16 v[60:63], v[136:139], v[152:155], v[60:63]
	v_mfma_f32_16x16x32_bf16 v[56:59], v[144:147], v[152:155], v[56:59]
	v_mfma_f32_16x16x32_bf16 v[44:47], v[136:139], v[160:163], v[44:47]
	v_mfma_f32_16x16x32_bf16 v[40:43], v[144:147], v[160:163], v[40:43]
	v_mfma_f32_16x16x32_bf16 v[28:31], v[136:139], v[198:201], v[28:31]
	v_mfma_f32_16x16x32_bf16 v[24:27], v[144:147], v[198:201], v[24:27]
	v_mfma_f32_16x16x32_bf16 v[12:15], v[136:139], v[224:227], v[12:15]
	v_mfma_f32_16x16x32_bf16 v[8:11], v[144:147], v[224:227], v[8:11]
	s_setprio 0
	s_barrier
	s_add_u32 s26, s26, s10
	s_addc_u32 s27, s27, s11
	s_add_i32 s51, s52, s34
	v_lshl_add_u64 v[210:211], s[26:27], 0, v[182:183]
	s_mov_b32 m0, s51
	v_lshl_add_u64 v[244:245], s[26:27], 0, v[178:179]
	global_load_lds_dwordx4 v[210:211], off
	s_add_i32 m0, s51, 0x2000
	s_nop 0
	global_load_lds_dwordx4 v[244:245], off
	s_waitcnt vmcnt(10)
	s_barrier
	s_setprio 1
	v_mfma_f32_16x16x32_bf16 v[52:55], v[228:231], v[148:151], v[52:55]
	v_mfma_f32_16x16x32_bf16 v[48:51], v[236:239], v[148:151], v[48:51]
	v_mfma_f32_16x16x32_bf16 v[36:39], v[228:231], v[156:159], v[36:39]
	v_mfma_f32_16x16x32_bf16 v[32:35], v[236:239], v[156:159], v[32:35]
	v_mfma_f32_16x16x32_bf16 v[20:23], v[228:231], v[194:197], v[20:23]
	v_mfma_f32_16x16x32_bf16 v[16:19], v[236:239], v[194:197], v[16:19]
	v_mfma_f32_16x16x32_bf16 v[4:7], v[228:231], v[202:205], v[4:7]
	v_mfma_f32_16x16x32_bf16 v[0:3], v[236:239], v[202:205], v[0:3]
	v_mfma_f32_16x16x32_bf16 v[52:55], v[232:235], v[152:155], v[52:55]
	v_mfma_f32_16x16x32_bf16 v[48:51], v[240:243], v[152:155], v[48:51]
	v_mfma_f32_16x16x32_bf16 v[36:39], v[232:235], v[160:163], v[36:39]
	v_mfma_f32_16x16x32_bf16 v[32:35], v[240:243], v[160:163], v[32:35]
	v_mfma_f32_16x16x32_bf16 v[20:23], v[232:235], v[198:201], v[20:23]
	v_mfma_f32_16x16x32_bf16 v[16:19], v[240:243], v[198:201], v[16:19]
	v_mfma_f32_16x16x32_bf16 v[4:7], v[232:235], v[224:227], v[4:7]
	v_mfma_f32_16x16x32_bf16 v[0:3], v[240:243], v[224:227], v[0:3]
	s_setprio 0
	s_add_i32 s26, 0, 0x18000
	v_add_u32_e32 v144, s26, v218
	s_barrier
	ds_read_b128 v[132:135], v144
	ds_read_b128 v[136:139], v144 offset:1024
	ds_read_b128 v[140:143], v144 offset:2048
	ds_read_b128 v[144:147], v144 offset:3072
	s_add_u32 s24, s24, s10
	s_addc_u32 s25, s25, s11
	s_mov_b32 m0, s37
	v_lshl_add_u64 v[228:229], s[24:25], 0, v[184:185]
	ds_read_b128 v[148:151], v220 offset:32768
	ds_read_b128 v[152:155], v220 offset:33792
	ds_read_b128 v[156:159], v220 offset:34816
	ds_read_b128 v[160:163], v220 offset:35840
	ds_read_b128 v[194:197], v220 offset:36864
	ds_read_b128 v[198:201], v220 offset:37888
	ds_read_b128 v[202:205], v220 offset:38912
	ds_read_b128 v[224:227], v220 offset:39936
	global_load_lds_dwordx4 v[228:229], off
	v_lshl_add_u64 v[228:229], s[24:25], 0, v[180:181]
	s_mov_b32 m0, s38
	s_nop 0
	global_load_lds_dwordx4 v[228:229], off
	s_waitcnt lgkmcnt(8)
	s_waitcnt vmcnt(10)
	s_barrier
	s_waitcnt lgkmcnt(0)
	s_setprio 1
	s_waitcnt lgkmcnt(0)
	v_mfma_f32_16x16x32_bf16 v[128:131], v[132:135], v[148:151], v[128:131]
	v_mfma_f32_16x16x32_bf16 v[124:127], v[140:143], v[148:151], v[124:127]
	v_mfma_f32_16x16x32_bf16 v[112:115], v[132:135], v[156:159], v[112:115]
	v_mfma_f32_16x16x32_bf16 v[108:111], v[140:143], v[156:159], v[108:111]
	v_mfma_f32_16x16x32_bf16 v[96:99], v[132:135], v[194:197], v[96:99]
	v_mfma_f32_16x16x32_bf16 v[92:95], v[140:143], v[194:197], v[92:95]
	v_mfma_f32_16x16x32_bf16 v[76:79], v[132:135], v[202:205], v[76:79]
	v_mfma_f32_16x16x32_bf16 v[72:75], v[140:143], v[202:205], v[72:75]
	v_mfma_f32_16x16x32_bf16 v[128:131], v[136:139], v[152:155], v[128:131]
	v_mfma_f32_16x16x32_bf16 v[124:127], v[144:147], v[152:155], v[124:127]
	v_mfma_f32_16x16x32_bf16 v[112:115], v[136:139], v[160:163], v[112:115]
	v_mfma_f32_16x16x32_bf16 v[108:111], v[144:147], v[160:163], v[108:111]
	v_mfma_f32_16x16x32_bf16 v[96:99], v[136:139], v[198:201], v[96:99]
	v_mfma_f32_16x16x32_bf16 v[92:95], v[144:147], v[198:201], v[92:95]
	v_mfma_f32_16x16x32_bf16 v[76:79], v[136:139], v[224:227], v[76:79]
	v_mfma_f32_16x16x32_bf16 v[72:75], v[144:147], v[224:227], v[72:75]
	s_setprio 0
	s_barrier
	s_add_i32 s24, 0, 0x1c000
	s_add_i32 s25, s26, s34
	v_add_u32_e32 v166, s24, v218
	v_lshl_add_u64 v[164:165], v[164:165], 0, s[88:89]
	s_mov_b32 m0, s25
	ds_read_b128 v[228:231], v166
	ds_read_b128 v[232:235], v166 offset:1024
	ds_read_b128 v[236:239], v166 offset:2048
	ds_read_b128 v[240:243], v166 offset:3072
	global_load_lds_dwordx4 v[164:165], off
	v_lshl_add_u64 v[164:165], v[170:171], 0, s[88:89]
	s_add_i32 m0, s25, 0x2000
	s_nop 0
	global_load_lds_dwordx4 v[164:165], off
	s_waitcnt vmcnt(10)
	s_barrier
	s_waitcnt lgkmcnt(0)
	s_setprio 1
	s_waitcnt lgkmcnt(0)
	v_mfma_f32_16x16x32_bf16 v[120:123], v[228:231], v[148:151], v[120:123]
	v_mfma_f32_16x16x32_bf16 v[116:119], v[236:239], v[148:151], v[116:119]
	v_mfma_f32_16x16x32_bf16 v[104:107], v[228:231], v[156:159], v[104:107]
	v_mfma_f32_16x16x32_bf16 v[100:103], v[236:239], v[156:159], v[100:103]
	v_mfma_f32_16x16x32_bf16 v[88:91], v[228:231], v[194:197], v[88:91]
	v_mfma_f32_16x16x32_bf16 v[84:87], v[236:239], v[194:197], v[84:87]
	v_mfma_f32_16x16x32_bf16 v[68:71], v[228:231], v[202:205], v[68:71]
	v_mfma_f32_16x16x32_bf16 v[64:67], v[236:239], v[202:205], v[64:67]
	v_mfma_f32_16x16x32_bf16 v[120:123], v[232:235], v[152:155], v[120:123]
	v_mfma_f32_16x16x32_bf16 v[116:119], v[240:243], v[152:155], v[116:119]
	v_mfma_f32_16x16x32_bf16 v[104:107], v[232:235], v[160:163], v[104:107]
	v_mfma_f32_16x16x32_bf16 v[100:103], v[240:243], v[160:163], v[100:103]
	v_mfma_f32_16x16x32_bf16 v[88:91], v[232:235], v[198:201], v[88:91]
	v_mfma_f32_16x16x32_bf16 v[84:87], v[240:243], v[198:201], v[84:87]
	v_mfma_f32_16x16x32_bf16 v[68:71], v[232:235], v[224:227], v[68:71]
	v_mfma_f32_16x16x32_bf16 v[64:67], v[240:243], v[224:227], v[64:67]
	s_setprio 0
	s_mov_b32 m0, s39
	v_lshl_add_u64 v[164:165], v[172:173], 0, s[88:89]
	s_barrier
	ds_read_b128 v[148:151], v220 offset:49152
	ds_read_b128 v[152:155], v220 offset:50176
	ds_read_b128 v[156:159], v220 offset:51200
	ds_read_b128 v[160:163], v220 offset:52224
	ds_read_b128 v[194:197], v220 offset:53248
	ds_read_b128 v[198:201], v220 offset:54272
	ds_read_b128 v[202:205], v220 offset:55296
	ds_read_b128 v[224:227], v220 offset:56320
	global_load_lds_dwordx4 v[164:165], off
	v_lshl_add_u64 v[164:165], v[206:207], 0, s[88:89]
	s_mov_b32 m0, s40
	s_nop 0
	global_load_lds_dwordx4 v[164:165], off
	s_barrier
	s_waitcnt lgkmcnt(0)
	s_setprio 1
	s_waitcnt lgkmcnt(0)
	v_mfma_f32_16x16x32_bf16 v[60:63], v[132:135], v[148:151], v[60:63]
	v_mfma_f32_16x16x32_bf16 v[56:59], v[140:143], v[148:151], v[56:59]
	v_mfma_f32_16x16x32_bf16 v[44:47], v[132:135], v[156:159], v[44:47]
	v_mfma_f32_16x16x32_bf16 v[40:43], v[140:143], v[156:159], v[40:43]
	v_mfma_f32_16x16x32_bf16 v[28:31], v[132:135], v[194:197], v[28:31]
	v_mfma_f32_16x16x32_bf16 v[24:27], v[140:143], v[194:197], v[24:27]
	v_mfma_f32_16x16x32_bf16 v[12:15], v[132:135], v[202:205], v[12:15]
	v_mfma_f32_16x16x32_bf16 v[8:11], v[140:143], v[202:205], v[8:11]
	v_mfma_f32_16x16x32_bf16 v[60:63], v[136:139], v[152:155], v[60:63]
	v_mfma_f32_16x16x32_bf16 v[56:59], v[144:147], v[152:155], v[56:59]
	v_mfma_f32_16x16x32_bf16 v[44:47], v[136:139], v[160:163], v[44:47]
	v_mfma_f32_16x16x32_bf16 v[40:43], v[144:147], v[160:163], v[40:43]
	v_mfma_f32_16x16x32_bf16 v[28:31], v[136:139], v[198:201], v[28:31]
	v_mfma_f32_16x16x32_bf16 v[24:27], v[144:147], v[198:201], v[24:27]
	v_mfma_f32_16x16x32_bf16 v[12:15], v[136:139], v[224:227], v[12:15]
	v_mfma_f32_16x16x32_bf16 v[8:11], v[144:147], v[224:227], v[8:11]
	s_setprio 0
	s_barrier
	s_add_i32 s24, s24, s34
	v_lshl_add_u64 v[132:133], v[210:211], 0, s[88:89]
	s_mov_b32 m0, s24
	s_nop 0
	global_load_lds_dwordx4 v[132:133], off
	v_lshl_add_u64 v[132:133], v[244:245], 0, s[88:89]
	s_add_i32 m0, s24, 0x2000
	s_nop 0
	global_load_lds_dwordx4 v[132:133], off
	s_waitcnt vmcnt(10)
	s_barrier
	s_setprio 1
	v_mfma_f32_16x16x32_bf16 v[52:55], v[228:231], v[148:151], v[52:55]
	v_mfma_f32_16x16x32_bf16 v[48:51], v[236:239], v[148:151], v[48:51]
	v_mfma_f32_16x16x32_bf16 v[36:39], v[228:231], v[156:159], v[36:39]
	v_mfma_f32_16x16x32_bf16 v[32:35], v[236:239], v[156:159], v[32:35]
	v_mfma_f32_16x16x32_bf16 v[20:23], v[228:231], v[194:197], v[20:23]
	v_mfma_f32_16x16x32_bf16 v[16:19], v[236:239], v[194:197], v[16:19]
	v_mfma_f32_16x16x32_bf16 v[4:7], v[228:231], v[202:205], v[4:7]
	v_mfma_f32_16x16x32_bf16 v[0:3], v[236:239], v[202:205], v[0:3]
	v_mfma_f32_16x16x32_bf16 v[52:55], v[232:235], v[152:155], v[52:55]
	v_mfma_f32_16x16x32_bf16 v[48:51], v[240:243], v[152:155], v[48:51]
	v_mfma_f32_16x16x32_bf16 v[36:39], v[232:235], v[160:163], v[36:39]
	v_mfma_f32_16x16x32_bf16 v[32:35], v[240:243], v[160:163], v[32:35]
	v_mfma_f32_16x16x32_bf16 v[20:23], v[232:235], v[198:201], v[20:23]
	v_mfma_f32_16x16x32_bf16 v[16:19], v[240:243], v[198:201], v[16:19]
	v_mfma_f32_16x16x32_bf16 v[4:7], v[232:235], v[224:227], v[4:7]
	v_mfma_f32_16x16x32_bf16 v[0:3], v[240:243], v[224:227], v[0:3]
	s_setprio 0
	s_add_u32 s19, s19, 0x100
	s_addc_u32 s49, s49, 0
	s_add_u32 s8, s8, 0x100
	s_addc_u32 s9, s9, 0
	s_mov_b32 s24, s50
	s_add_i32 s50, s24, 2
	s_add_u32 s26, s8, 0x80
	s_addc_u32 s25, s9, 0
	s_cmp_ge_i32 s24, s41
	s_barrier
	s_cbranch_scc0 .Lp6_rot
	s_movk_i32 s52, 0x880
	s_movk_i32 s50, 0x110
	v_readlane_b32 s51, v254, 48
